# same-XCD tails plus LDS reads of unused operand halves skipped in half/quarter mode
# baseline (speedup 1.0000x reference)
.Lh9_q0:
	s_setprio 0
	s_barrier
	s_mov_b64 s[84:85], s[56:57]
	s_add_i32 s83, s83, s25
	s_cmp_lg_u32 s100, 0
	s_cbranch_scc1 .Lh9_m0_r
	ds_read_b128 v[162:165], v216 offset:16384
	ds_read_b128 v[166:169], v216 offset:17408
	ds_read_b128 v[194:197], v216 offset:18432
	ds_read_b128 v[198:201], v216 offset:19456
	ds_read_b128 v[202:205], v216 offset:20480
	ds_read_b128 v[206:209], v216 offset:21504
	ds_read_b128 v[218:221], v216 offset:22528
	ds_read_b128 v[222:225], v216 offset:23552

.Lh9_q1:
	s_setprio 0
	s_barrier
	s_add_u32 s18, s56, 0x80
	s_addc_u32 s19, s57, 0
	s_add_i32 s83, s83, s25
	s_cmp_lg_u32 s100, 0
	s_cbranch_scc1 .Lh9_m1_r
	ds_read_b128 v[162:165], v216 offset:49152
	ds_read_b128 v[166:169], v216 offset:50176
	ds_read_b128 v[194:197], v216 offset:51200
	ds_read_b128 v[198:201], v216 offset:52224
	ds_read_b128 v[202:205], v216 offset:53248
	ds_read_b128 v[206:209], v216 offset:54272
	ds_read_b128 v[218:221], v216 offset:55296
	ds_read_b128 v[222:225], v216 offset:56320
